# lru input stage: the three 11-load batches of the main loop issued under one wait (one far-memory round trip instead of up to three)
# speedup vs baseline: 1.0056x; 1.0056x over previous
; __device__ __forceinline__ float bf2f(bf16_t v) { return __uint_as_float(((unsigned)v) << 16); }
; __device__ void lru_local_unit(const Params& p, unsigned char* smem, int unit) {
;     ...
; #pragma unroll 11
;   for (int e = tid; e < 131 * 64; e += HTHR) {
;     const int r = e >> 6, j = e & 63, tt = r - 3;
;     float v = 0.f;
;     if (c * 128 + tt >= 0) v = bf2f(proj[(size_t)(t0 + tt) * LDP + ch0 + j]);
;     R1[e] = v;
;   }
.LBB0_507:
	s_mov_b64 s[66:67], exec
	s_movk_i32 s12, 0x15bf
	s_mov_b32 s3, 0
	v_add_u32_e32 v32, s3, v5
	v_cmp_gt_i32_e32 vcc, v32, v4
	v_mov_b32_e32 v140, 0
	s_and_saveexec_b64 s[78:79], vcc
	v_add_u32_e32 v32, s3, v29
	v_mad_i64_i32 v[32:33], s[12:13], v32, s89, v[2:3]
	global_load_ushort v140, v[32:33], off
	s_or_b64 exec, exec, s[78:79]
	v_add_u32_e32 v32, s3, v27
	v_cmp_gt_i32_e32 vcc, v32, v4
	v_mov_b32_e32 v141, 0
	s_and_saveexec_b64 s[78:79], vcc
	v_add_u32_e32 v32, s3, v28
	v_mad_i64_i32 v[32:33], s[12:13], v32, s89, v[2:3]
	global_load_ushort v141, v[32:33], off
	s_or_b64 exec, exec, s[78:79]
	v_add_u32_e32 v32, s3, v24
	v_cmp_gt_i32_e32 vcc, v32, v4
	v_mov_b32_e32 v142, 0
	s_and_saveexec_b64 s[78:79], vcc
	v_add_u32_e32 v32, s3, v25
	v_mad_i64_i32 v[32:33], s[12:13], v32, s89, v[2:3]
	global_load_ushort v142, v[32:33], off
	s_or_b64 exec, exec, s[78:79]
	v_add_u32_e32 v32, s3, v22
	v_cmp_gt_i32_e32 vcc, v32, v4
	v_mov_b32_e32 v143, 0
	s_and_saveexec_b64 s[78:79], vcc
	v_add_u32_e32 v32, s3, v23
	v_mad_i64_i32 v[32:33], s[12:13], v32, s89, v[2:3]
	global_load_ushort v143, v[32:33], off
	s_or_b64 exec, exec, s[78:79]
	v_add_u32_e32 v32, s3, v20
	v_cmp_gt_i32_e32 vcc, v32, v4
	v_mov_b32_e32 v144, 0
	s_and_saveexec_b64 s[78:79], vcc
	v_add_u32_e32 v32, s3, v21
	v_mad_i64_i32 v[32:33], s[12:13], v32, s89, v[2:3]
	global_load_ushort v144, v[32:33], off
	s_or_b64 exec, exec, s[78:79]
	v_add_u32_e32 v32, s3, v18
	v_cmp_gt_i32_e32 vcc, v32, v4
	v_mov_b32_e32 v145, 0
	s_and_saveexec_b64 s[78:79], vcc
	v_add_u32_e32 v32, s3, v19
	v_mad_i64_i32 v[32:33], s[12:13], v32, s89, v[2:3]
	global_load_ushort v145, v[32:33], off
	s_or_b64 exec, exec, s[78:79]
	v_add_u32_e32 v32, s3, v15
	v_cmp_gt_i32_e32 vcc, v32, v4
	v_mov_b32_e32 v146, 0
	s_and_saveexec_b64 s[78:79], vcc
	v_add_u32_e32 v32, s3, v17
	v_mad_i64_i32 v[32:33], s[12:13], v32, s89, v[2:3]
	global_load_ushort v146, v[32:33], off
	s_or_b64 exec, exec, s[78:79]
	v_add_u32_e32 v32, s3, v13
	v_cmp_gt_i32_e32 vcc, v32, v4
	v_mov_b32_e32 v147, 0
	s_and_saveexec_b64 s[78:79], vcc
	v_add_u32_e32 v32, s3, v14
	v_mad_i64_i32 v[32:33], s[12:13], v32, s89, v[2:3]
	global_load_ushort v147, v[32:33], off
	s_or_b64 exec, exec, s[78:79]
	v_add_u32_e32 v32, s3, v11
	v_cmp_gt_i32_e32 vcc, v32, v4
	v_mov_b32_e32 v148, 0
	s_and_saveexec_b64 s[78:79], vcc
	v_add_u32_e32 v32, s3, v12
	v_mad_i64_i32 v[32:33], s[12:13], v32, s89, v[2:3]
	global_load_ushort v148, v[32:33], off
	s_or_b64 exec, exec, s[78:79]
	v_add_u32_e32 v32, s3, v9
	v_cmp_gt_i32_e32 vcc, v32, v4
	v_mov_b32_e32 v149, 0
	s_and_saveexec_b64 s[78:79], vcc
	v_add_u32_e32 v32, s3, v10
	v_mad_i64_i32 v[32:33], s[12:13], v32, s89, v[2:3]
	global_load_ushort v149, v[32:33], off
	s_or_b64 exec, exec, s[78:79]
	v_add_u32_e32 v32, s3, v7
	v_cmp_gt_i32_e32 vcc, v32, v4
	v_mov_b32_e32 v150, 0
	s_and_saveexec_b64 s[78:79], vcc
	v_add_u32_e32 v32, s3, v8
	v_mad_i64_i32 v[32:33], s[12:13], v32, s89, v[2:3]
	global_load_ushort v150, v[32:33], off
	s_or_b64 exec, exec, s[78:79]
	v_add_u32_e32 v6, 0xb00, v6
	s_movk_i32 s12, 0x15bf
	v_cmp_ge_u32_e32 vcc, s12, v6
	s_and_b64 s[72:73], exec, vcc
	s_mov_b64 exec, s[72:73]
	s_mov_b32 s3, 44
	v_add_u32_e32 v32, s3, v5
	v_cmp_gt_i32_e32 vcc, v32, v4
	v_mov_b32_e32 v193, 0
	s_and_saveexec_b64 s[78:79], vcc
	v_add_u32_e32 v32, s3, v29
	v_mad_i64_i32 v[32:33], s[12:13], v32, s89, v[2:3]
	global_load_ushort v193, v[32:33], off
	s_or_b64 exec, exec, s[78:79]
	v_add_u32_e32 v32, s3, v27
	v_cmp_gt_i32_e32 vcc, v32, v4
	v_mov_b32_e32 v194, 0
	s_and_saveexec_b64 s[78:79], vcc
	v_add_u32_e32 v32, s3, v28
	v_mad_i64_i32 v[32:33], s[12:13], v32, s89, v[2:3]
	global_load_ushort v194, v[32:33], off
	s_or_b64 exec, exec, s[78:79]
	v_add_u32_e32 v32, s3, v24
	v_cmp_gt_i32_e32 vcc, v32, v4
	v_mov_b32_e32 v195, 0
	s_and_saveexec_b64 s[78:79], vcc
	v_add_u32_e32 v32, s3, v25
	v_mad_i64_i32 v[32:33], s[12:13], v32, s89, v[2:3]
	global_load_ushort v195, v[32:33], off
	s_or_b64 exec, exec, s[78:79]
	v_add_u32_e32 v32, s3, v22
	v_cmp_gt_i32_e32 vcc, v32, v4
	v_mov_b32_e32 v196, 0
	s_and_saveexec_b64 s[78:79], vcc
	v_add_u32_e32 v32, s3, v23
	v_mad_i64_i32 v[32:33], s[12:13], v32, s89, v[2:3]
	global_load_ushort v196, v[32:33], off
	s_or_b64 exec, exec, s[78:79]
	v_add_u32_e32 v32, s3, v20
	v_cmp_gt_i32_e32 vcc, v32, v4
	v_mov_b32_e32 v197, 0
	s_and_saveexec_b64 s[78:79], vcc
	v_add_u32_e32 v32, s3, v21
	v_mad_i64_i32 v[32:33], s[12:13], v32, s89, v[2:3]
	global_load_ushort v197, v[32:33], off
	s_or_b64 exec, exec, s[78:79]
	v_add_u32_e32 v32, s3, v18
	v_cmp_gt_i32_e32 vcc, v32, v4
	v_mov_b32_e32 v198, 0
	s_and_saveexec_b64 s[78:79], vcc
	v_add_u32_e32 v32, s3, v19
	v_mad_i64_i32 v[32:33], s[12:13], v32, s89, v[2:3]
	global_load_ushort v198, v[32:33], off
	s_or_b64 exec, exec, s[78:79]
	v_add_u32_e32 v32, s3, v15
	v_cmp_gt_i32_e32 vcc, v32, v4
	v_mov_b32_e32 v199, 0
	s_and_saveexec_b64 s[78:79], vcc
	v_add_u32_e32 v32, s3, v17
	v_mad_i64_i32 v[32:33], s[12:13], v32, s89, v[2:3]
	global_load_ushort v199, v[32:33], off
	s_or_b64 exec, exec, s[78:79]
	v_add_u32_e32 v32, s3, v13
	v_cmp_gt_i32_e32 vcc, v32, v4
	v_mov_b32_e32 v200, 0
	s_and_saveexec_b64 s[78:79], vcc
	v_add_u32_e32 v32, s3, v14
	v_mad_i64_i32 v[32:33], s[12:13], v32, s89, v[2:3]
	global_load_ushort v200, v[32:33], off
	s_or_b64 exec, exec, s[78:79]
	v_add_u32_e32 v32, s3, v11
	v_cmp_gt_i32_e32 vcc, v32, v4
	v_mov_b32_e32 v201, 0
	s_and_saveexec_b64 s[78:79], vcc
	v_add_u32_e32 v32, s3, v12
	v_mad_i64_i32 v[32:33], s[12:13], v32, s89, v[2:3]
	global_load_ushort v201, v[32:33], off
	s_or_b64 exec, exec, s[78:79]
	v_add_u32_e32 v32, s3, v9
	v_cmp_gt_i32_e32 vcc, v32, v4
; __device__ __forceinline__ float bf2f(bf16_t v) { return __uint_as_float(((unsigned)v) << 16); }
; __device__ void lru_local_unit(const Params& p, unsigned char* smem, int unit) {
;     ...
; #pragma unroll 11
;   for (int e = tid; e < 131 * 64; e += HTHR) {
;     const int r = e >> 6, j = e & 63, tt = r - 3;
;     float v = 0.f;
;     if (c * 128 + tt >= 0) v = bf2f(proj[(size_t)(t0 + tt) * LDP + ch0 + j]);
;     R1[e] = v;
;   }
	v_mov_b32_e32 v202, 0
	s_and_saveexec_b64 s[78:79], vcc
	v_add_u32_e32 v32, s3, v10
	v_mad_i64_i32 v[32:33], s[12:13], v32, s89, v[2:3]
	global_load_ushort v202, v[32:33], off
	s_or_b64 exec, exec, s[78:79]
	v_add_u32_e32 v32, s3, v7
	v_cmp_gt_i32_e32 vcc, v32, v4
	v_mov_b32_e32 v203, 0
	s_and_saveexec_b64 s[78:79], vcc
	v_add_u32_e32 v32, s3, v8
	v_mad_i64_i32 v[32:33], s[12:13], v32, s89, v[2:3]
	global_load_ushort v203, v[32:33], off
	s_or_b64 exec, exec, s[78:79]
	v_add_u32_e32 v6, 0xb00, v6
	s_movk_i32 s12, 0x15bf
	v_cmp_ge_u32_e32 vcc, s12, v6
	s_and_b64 s[74:75], exec, vcc
	s_mov_b64 exec, s[74:75]
	s_mov_b32 s3, 88
	v_add_u32_e32 v32, s3, v5
	v_cmp_gt_i32_e32 vcc, v32, v4
	v_mov_b32_e32 v204, 0
	s_and_saveexec_b64 s[78:79], vcc
	v_add_u32_e32 v32, s3, v29
	v_mad_i64_i32 v[32:33], s[12:13], v32, s89, v[2:3]
	global_load_ushort v204, v[32:33], off
	s_or_b64 exec, exec, s[78:79]
	v_add_u32_e32 v32, s3, v27
	v_cmp_gt_i32_e32 vcc, v32, v4
	v_mov_b32_e32 v205, 0
	s_and_saveexec_b64 s[78:79], vcc
	v_add_u32_e32 v32, s3, v28
	v_mad_i64_i32 v[32:33], s[12:13], v32, s89, v[2:3]
	global_load_ushort v205, v[32:33], off
	s_or_b64 exec, exec, s[78:79]
	v_add_u32_e32 v32, s3, v24
	v_cmp_gt_i32_e32 vcc, v32, v4
	v_mov_b32_e32 v206, 0
	s_and_saveexec_b64 s[78:79], vcc
	v_add_u32_e32 v32, s3, v25
	v_mad_i64_i32 v[32:33], s[12:13], v32, s89, v[2:3]
	global_load_ushort v206, v[32:33], off
	s_or_b64 exec, exec, s[78:79]
	v_add_u32_e32 v32, s3, v22
	v_cmp_gt_i32_e32 vcc, v32, v4
	v_mov_b32_e32 v207, 0
	s_and_saveexec_b64 s[78:79], vcc
	v_add_u32_e32 v32, s3, v23
	v_mad_i64_i32 v[32:33], s[12:13], v32, s89, v[2:3]
	global_load_ushort v207, v[32:33], off
	s_or_b64 exec, exec, s[78:79]
	v_add_u32_e32 v32, s3, v20
	v_cmp_gt_i32_e32 vcc, v32, v4
	v_mov_b32_e32 v208, 0
	s_and_saveexec_b64 s[78:79], vcc
	v_add_u32_e32 v32, s3, v21
	v_mad_i64_i32 v[32:33], s[12:13], v32, s89, v[2:3]
	global_load_ushort v208, v[32:33], off
	s_or_b64 exec, exec, s[78:79]
	v_add_u32_e32 v32, s3, v18
	v_cmp_gt_i32_e32 vcc, v32, v4
	v_mov_b32_e32 v209, 0
	s_and_saveexec_b64 s[78:79], vcc
	v_add_u32_e32 v32, s3, v19
	v_mad_i64_i32 v[32:33], s[12:13], v32, s89, v[2:3]
	global_load_ushort v209, v[32:33], off
	s_or_b64 exec, exec, s[78:79]
	v_add_u32_e32 v32, s3, v15
	v_cmp_gt_i32_e32 vcc, v32, v4
	v_mov_b32_e32 v210, 0
	s_and_saveexec_b64 s[78:79], vcc
	v_add_u32_e32 v32, s3, v17
	v_mad_i64_i32 v[32:33], s[12:13], v32, s89, v[2:3]
	global_load_ushort v210, v[32:33], off
	s_or_b64 exec, exec, s[78:79]
	v_add_u32_e32 v32, s3, v13
	v_cmp_gt_i32_e32 vcc, v32, v4
	v_mov_b32_e32 v211, 0
	s_and_saveexec_b64 s[78:79], vcc
	v_add_u32_e32 v32, s3, v14
	v_mad_i64_i32 v[32:33], s[12:13], v32, s89, v[2:3]
	global_load_ushort v211, v[32:33], off
	s_or_b64 exec, exec, s[78:79]
	v_add_u32_e32 v32, s3, v11
	v_cmp_gt_i32_e32 vcc, v32, v4
	v_mov_b32_e32 v212, 0
	s_and_saveexec_b64 s[78:79], vcc
	v_add_u32_e32 v32, s3, v12
	v_mad_i64_i32 v[32:33], s[12:13], v32, s89, v[2:3]
	global_load_ushort v212, v[32:33], off
	s_or_b64 exec, exec, s[78:79]
	v_add_u32_e32 v32, s3, v9
	v_cmp_gt_i32_e32 vcc, v32, v4
	v_mov_b32_e32 v213, 0
	s_and_saveexec_b64 s[78:79], vcc
	v_add_u32_e32 v32, s3, v10
	v_mad_i64_i32 v[32:33], s[12:13], v32, s89, v[2:3]
	global_load_ushort v213, v[32:33], off
	s_or_b64 exec, exec, s[78:79]
	v_add_u32_e32 v32, s3, v7
	v_cmp_gt_i32_e32 vcc, v32, v4
	v_mov_b32_e32 v214, 0
	s_and_saveexec_b64 s[78:79], vcc
	v_add_u32_e32 v32, s3, v8
	v_mad_i64_i32 v[32:33], s[12:13], v32, s89, v[2:3]
	global_load_ushort v214, v[32:33], off
	s_or_b64 exec, exec, s[78:79]
	s_mov_b64 exec, s[66:67]
	s_waitcnt vmcnt(0)
	v_lshlrev_b32_e32 v140, 16, v140
	ds_write_b32 v26, v140
	v_lshlrev_b32_e32 v141, 16, v141
	ds_write_b32 v26, v141 offset:1024
	v_lshlrev_b32_e32 v142, 16, v142
	ds_write_b32 v26, v142 offset:2048
	v_lshlrev_b32_e32 v143, 16, v143
	ds_write_b32 v26, v143 offset:3072
	v_lshlrev_b32_e32 v144, 16, v144
	ds_write_b32 v26, v144 offset:4096
	v_lshlrev_b32_e32 v145, 16, v145
	ds_write_b32 v26, v145 offset:5120
	v_lshlrev_b32_e32 v146, 16, v146
	ds_write_b32 v26, v146 offset:6144
	v_lshlrev_b32_e32 v147, 16, v147
	ds_write_b32 v26, v147 offset:7168
	v_lshlrev_b32_e32 v148, 16, v148
	ds_write_b32 v26, v148 offset:8192
	v_lshlrev_b32_e32 v149, 16, v149
	ds_write_b32 v26, v149 offset:9216
	v_lshlrev_b32_e32 v150, 16, v150
	ds_write_b32 v26, v150 offset:10240
	s_mov_b64 exec, s[72:73]
	v_lshlrev_b32_e32 v193, 16, v193
	ds_write_b32 v26, v193 offset:11264
	v_lshlrev_b32_e32 v194, 16, v194
	ds_write_b32 v26, v194 offset:12288
	v_lshlrev_b32_e32 v195, 16, v195
	ds_write_b32 v26, v195 offset:13312
	v_lshlrev_b32_e32 v196, 16, v196
	ds_write_b32 v26, v196 offset:14336
	v_lshlrev_b32_e32 v197, 16, v197
	ds_write_b32 v26, v197 offset:15360
	v_lshlrev_b32_e32 v198, 16, v198
	ds_write_b32 v26, v198 offset:16384
	v_lshlrev_b32_e32 v199, 16, v199
	ds_write_b32 v26, v199 offset:17408
	v_lshlrev_b32_e32 v200, 16, v200
	ds_write_b32 v26, v200 offset:18432
	v_lshlrev_b32_e32 v201, 16, v201
	ds_write_b32 v26, v201 offset:19456
	v_lshlrev_b32_e32 v202, 16, v202
	ds_write_b32 v26, v202 offset:20480
	v_lshlrev_b32_e32 v203, 16, v203
	ds_write_b32 v26, v203 offset:21504
	s_mov_b64 exec, s[74:75]
	v_lshlrev_b32_e32 v204, 16, v204
	ds_write_b32 v26, v204 offset:22528
	v_lshlrev_b32_e32 v205, 16, v205
	ds_write_b32 v26, v205 offset:23552
	v_lshlrev_b32_e32 v206, 16, v206
	ds_write_b32 v26, v206 offset:24576
	v_lshlrev_b32_e32 v207, 16, v207
	ds_write_b32 v26, v207 offset:25600
	v_lshlrev_b32_e32 v208, 16, v208
	ds_write_b32 v26, v208 offset:26624
	v_lshlrev_b32_e32 v209, 16, v209
	ds_write_b32 v26, v209 offset:27648
	v_lshlrev_b32_e32 v210, 16, v210
	ds_write_b32 v26, v210 offset:28672
	v_lshlrev_b32_e32 v211, 16, v211
	ds_write_b32 v26, v211 offset:29696
	v_lshlrev_b32_e32 v212, 16, v212
	ds_write_b32 v26, v212 offset:30720
	v_lshlrev_b32_e32 v213, 16, v213
	ds_write_b32 v26, v213 offset:31744
	v_lshlrev_b32_e32 v214, 16, v214
	ds_write_b32 v26, v214 offset:32768
	s_mov_b64 exec, s[66:67]
	s_mov_b64 s[66:67], 0
